# same as previous with 8-byte padding kept (s_nop beside the added wait)
# speedup vs baseline: 1.0071x; 1.0071x over previous
; __device__ __forceinline__ void filter_item(const Params& p, int l, int Lf, int t0, float* dst, float* hidT  , int wid0) {
;     ...
; #pragma unroll 16
;     for (int j = 0; j < 64; ++j) {
;         const float wa = w3[j * 1024 + tid], wb = w3[j * 1024 + 512 + tid];
; #pragma unroll
;         for (int g = 0; g < 8; ++g) { const f32x4 hv = *(const f32x4*)(hidT + j * 32 + 4 * g);
; #pragma unroll
;             for (int i = 0; i < 4; ++i) { acc0[4 * g + i] += hv[i] * wa; acc1[4 * g + i] += hv[i] * wb; } }
;     }
.Lw3_719_loop:
	s_waitcnt lgkmcnt(7)
	s_nop 0
	ds_read_b128 v[142:145], v186 offset:128
	ds_read_b128 v[146:149], v186 offset:144
	ds_read_b128 v[150:153], v186 offset:160
	ds_read_b128 v[154:157], v186 offset:176
	ds_read_b128 v[158:161], v186 offset:192
	ds_read_b128 v[162:165], v186 offset:208
	ds_read_b128 v[166:169], v186 offset:224
	ds_read_b128 v[170:173], v186 offset:240
	s_waitcnt vmcnt(2) lgkmcnt(8)
	v_pk_fma_f32 v[68:69], v[174:175], v[110:111], v[68:69] op_sel_hi:[0,1,1]
	v_pk_fma_f32 v[62:63], v[176:177], v[110:111], v[62:63] op_sel_hi:[0,1,1]
	v_pk_fma_f32 v[66:67], v[174:175], v[112:113], v[66:67] op_sel_hi:[0,1,1]
	v_pk_fma_f32 v[64:65], v[176:177], v[112:113], v[64:65] op_sel_hi:[0,1,1]
	v_pk_fma_f32 v[60:61], v[174:175], v[114:115], v[60:61] op_sel_hi:[0,1,1]
	v_pk_fma_f32 v[56:57], v[176:177], v[114:115], v[56:57] op_sel_hi:[0,1,1]
	v_pk_fma_f32 v[58:59], v[174:175], v[116:117], v[58:59] op_sel_hi:[0,1,1]
	v_pk_fma_f32 v[54:55], v[176:177], v[116:117], v[54:55] op_sel_hi:[0,1,1]
	v_pk_fma_f32 v[52:53], v[174:175], v[118:119], v[52:53] op_sel_hi:[0,1,1]
	v_pk_fma_f32 v[48:49], v[176:177], v[118:119], v[48:49] op_sel_hi:[0,1,1]
	v_pk_fma_f32 v[50:51], v[174:175], v[120:121], v[50:51] op_sel_hi:[0,1,1]
	v_pk_fma_f32 v[46:47], v[176:177], v[120:121], v[46:47] op_sel_hi:[0,1,1]
	v_pk_fma_f32 v[44:45], v[174:175], v[122:123], v[44:45] op_sel_hi:[0,1,1]
	v_pk_fma_f32 v[40:41], v[176:177], v[122:123], v[40:41] op_sel_hi:[0,1,1]
	v_pk_fma_f32 v[42:43], v[174:175], v[124:125], v[42:43] op_sel_hi:[0,1,1]
	v_pk_fma_f32 v[38:39], v[176:177], v[124:125], v[38:39] op_sel_hi:[0,1,1]
	v_pk_fma_f32 v[36:37], v[174:175], v[126:127], v[36:37] op_sel_hi:[0,1,1]
	v_pk_fma_f32 v[32:33], v[176:177], v[126:127], v[32:33] op_sel_hi:[0,1,1]
	v_pk_fma_f32 v[34:35], v[174:175], v[128:129], v[34:35] op_sel_hi:[0,1,1]
	v_pk_fma_f32 v[30:31], v[176:177], v[128:129], v[30:31] op_sel_hi:[0,1,1]
	v_pk_fma_f32 v[28:29], v[174:175], v[130:131], v[28:29] op_sel_hi:[0,1,1]
	v_pk_fma_f32 v[24:25], v[176:177], v[130:131], v[24:25] op_sel_hi:[0,1,1]
	v_pk_fma_f32 v[26:27], v[174:175], v[132:133], v[26:27] op_sel_hi:[0,1,1]
	v_pk_fma_f32 v[22:23], v[176:177], v[132:133], v[22:23] op_sel_hi:[0,1,1]
	v_pk_fma_f32 v[20:21], v[174:175], v[134:135], v[20:21] op_sel_hi:[0,1,1]
	v_pk_fma_f32 v[14:15], v[176:177], v[134:135], v[14:15] op_sel_hi:[0,1,1]
	v_pk_fma_f32 v[18:19], v[174:175], v[136:137], v[18:19] op_sel_hi:[0,1,1]
	v_pk_fma_f32 v[16:17], v[176:177], v[136:137], v[16:17] op_sel_hi:[0,1,1]
	v_pk_fma_f32 v[10:11], v[174:175], v[138:139], v[10:11] op_sel_hi:[0,1,1]
	v_pk_fma_f32 v[6:7], v[176:177], v[138:139], v[6:7] op_sel_hi:[0,1,1]
	v_pk_fma_f32 v[12:13], v[174:175], v[140:141], v[12:13] op_sel_hi:[0,1,1]
	v_pk_fma_f32 v[8:9], v[176:177], v[140:141], v[8:9] op_sel_hi:[0,1,1]
	global_load_dword v174, v[182:183], off
	global_load_dword v176, v[182:183], off offset:2048
	v_lshl_add_u64 v[182:183], v[182:183], 0, vcc
	s_waitcnt lgkmcnt(7)
	s_nop 0
	ds_read_b128 v[110:113], v186 offset:256
	ds_read_b128 v[114:117], v186 offset:272
	ds_read_b128 v[118:121], v186 offset:288
	ds_read_b128 v[122:125], v186 offset:304
	ds_read_b128 v[126:129], v186 offset:320
	ds_read_b128 v[130:133], v186 offset:336
	ds_read_b128 v[134:137], v186 offset:352
	ds_read_b128 v[138:141], v186 offset:368
	s_waitcnt vmcnt(2) lgkmcnt(8)
	v_pk_fma_f32 v[68:69], v[178:179], v[142:143], v[68:69] op_sel_hi:[0,1,1]
	v_pk_fma_f32 v[62:63], v[180:181], v[142:143], v[62:63] op_sel_hi:[0,1,1]
	v_pk_fma_f32 v[66:67], v[178:179], v[144:145], v[66:67] op_sel_hi:[0,1,1]
	v_pk_fma_f32 v[64:65], v[180:181], v[144:145], v[64:65] op_sel_hi:[0,1,1]
	v_pk_fma_f32 v[60:61], v[178:179], v[146:147], v[60:61] op_sel_hi:[0,1,1]
	v_pk_fma_f32 v[56:57], v[180:181], v[146:147], v[56:57] op_sel_hi:[0,1,1]
	v_pk_fma_f32 v[58:59], v[178:179], v[148:149], v[58:59] op_sel_hi:[0,1,1]
	v_pk_fma_f32 v[54:55], v[180:181], v[148:149], v[54:55] op_sel_hi:[0,1,1]
	v_pk_fma_f32 v[52:53], v[178:179], v[150:151], v[52:53] op_sel_hi:[0,1,1]
	v_pk_fma_f32 v[48:49], v[180:181], v[150:151], v[48:49] op_sel_hi:[0,1,1]
	v_pk_fma_f32 v[50:51], v[178:179], v[152:153], v[50:51] op_sel_hi:[0,1,1]
	v_pk_fma_f32 v[46:47], v[180:181], v[152:153], v[46:47] op_sel_hi:[0,1,1]
	v_pk_fma_f32 v[44:45], v[178:179], v[154:155], v[44:45] op_sel_hi:[0,1,1]
	v_pk_fma_f32 v[40:41], v[180:181], v[154:155], v[40:41] op_sel_hi:[0,1,1]
	v_pk_fma_f32 v[42:43], v[178:179], v[156:157], v[42:43] op_sel_hi:[0,1,1]
	v_pk_fma_f32 v[38:39], v[180:181], v[156:157], v[38:39] op_sel_hi:[0,1,1]
	v_pk_fma_f32 v[36:37], v[178:179], v[158:159], v[36:37] op_sel_hi:[0,1,1]
	v_pk_fma_f32 v[32:33], v[180:181], v[158:159], v[32:33] op_sel_hi:[0,1,1]
	v_pk_fma_f32 v[34:35], v[178:179], v[160:161], v[34:35] op_sel_hi:[0,1,1]
	v_pk_fma_f32 v[30:31], v[180:181], v[160:161], v[30:31] op_sel_hi:[0,1,1]
	v_pk_fma_f32 v[28:29], v[178:179], v[162:163], v[28:29] op_sel_hi:[0,1,1]
	v_pk_fma_f32 v[24:25], v[180:181], v[162:163], v[24:25] op_sel_hi:[0,1,1]
	v_pk_fma_f32 v[26:27], v[178:179], v[164:165], v[26:27] op_sel_hi:[0,1,1]
	v_pk_fma_f32 v[22:23], v[180:181], v[164:165], v[22:23] op_sel_hi:[0,1,1]
	v_pk_fma_f32 v[20:21], v[178:179], v[166:167], v[20:21] op_sel_hi:[0,1,1]
	v_pk_fma_f32 v[14:15], v[180:181], v[166:167], v[14:15] op_sel_hi:[0,1,1]
	v_pk_fma_f32 v[18:19], v[178:179], v[168:169], v[18:19] op_sel_hi:[0,1,1]
	v_pk_fma_f32 v[16:17], v[180:181], v[168:169], v[16:17] op_sel_hi:[0,1,1]
	v_pk_fma_f32 v[10:11], v[178:179], v[170:171], v[10:11] op_sel_hi:[0,1,1]
	v_pk_fma_f32 v[6:7], v[180:181], v[170:171], v[6:7] op_sel_hi:[0,1,1]
	v_pk_fma_f32 v[12:13], v[178:179], v[172:173], v[12:13] op_sel_hi:[0,1,1]
	v_pk_fma_f32 v[8:9], v[180:181], v[172:173], v[8:9] op_sel_hi:[0,1,1]
	global_load_dword v178, v[182:183], off
	global_load_dword v180, v[182:183], off offset:2048
	v_lshl_add_u64 v[182:183], v[182:183], 0, vcc
	v_add_u32_e32 v186, 0x100, v186
	s_add_i32 s1, s1, -1
	s_cmp_lg_u32 s1, 0
	s_cbranch_scc1 .Lw3_719_loop
; __device__ __forceinline__ void filter_item(const Params& p, int l, int Lf, int t0, float* dst, float* hidT  , int wid0) {
;     ...
; #pragma unroll 16
;     for (int j = 0; j < 64; ++j) {
;         const float wa = w3[j * 1024 + tid], wb = w3[j * 1024 + 512 + tid];
; #pragma unroll
;         for (int g = 0; g < 8; ++g) { const f32x4 hv = *(const f32x4*)(hidT + j * 32 + 4 * g);
; #pragma unroll
;             for (int i = 0; i < 4; ++i) { acc0[4 * g + i] += hv[i] * wa; acc1[4 * g + i] += hv[i] * wb; } }
;     }
;     const float dmin = -3.0701134573253945f, dmax = -15.350567286626973f;
;     const float delta = fabsf(dmin + (float)tid * ((dmax - dmin) / 511.f));
; #pragma unroll
;     for (int g = 0; g < 8; ++g) { f32x4 o0, o1;
; #pragma unroll
;         for (int i = 0; i < 4; ++i) { const float tn = (float)(t0 + 4 * g + i) / (float)(Lf - 1); const float wdw = __expf(-tn * delta); o0[i] = acc0[4 * g + i] * wdw; o1[i] = acc1[4 * g + i] * wdw; }
	s_waitcnt lgkmcnt(7)
	s_nop 0
	ds_read_b128 v[142:145], v186 offset:128
	ds_read_b128 v[146:149], v186 offset:144
	ds_read_b128 v[150:153], v186 offset:160
	ds_read_b128 v[154:157], v186 offset:176
	ds_read_b128 v[158:161], v186 offset:192
	ds_read_b128 v[162:165], v186 offset:208
	ds_read_b128 v[166:169], v186 offset:224
	ds_read_b128 v[170:173], v186 offset:240
	s_waitcnt vmcnt(2) lgkmcnt(8)
	v_pk_fma_f32 v[68:69], v[174:175], v[110:111], v[68:69] op_sel_hi:[0,1,1]
	v_pk_fma_f32 v[62:63], v[176:177], v[110:111], v[62:63] op_sel_hi:[0,1,1]
	v_pk_fma_f32 v[66:67], v[174:175], v[112:113], v[66:67] op_sel_hi:[0,1,1]
	v_pk_fma_f32 v[64:65], v[176:177], v[112:113], v[64:65] op_sel_hi:[0,1,1]
	v_pk_fma_f32 v[60:61], v[174:175], v[114:115], v[60:61] op_sel_hi:[0,1,1]
	v_pk_fma_f32 v[56:57], v[176:177], v[114:115], v[56:57] op_sel_hi:[0,1,1]
	v_pk_fma_f32 v[58:59], v[174:175], v[116:117], v[58:59] op_sel_hi:[0,1,1]
	v_pk_fma_f32 v[54:55], v[176:177], v[116:117], v[54:55] op_sel_hi:[0,1,1]
	v_pk_fma_f32 v[52:53], v[174:175], v[118:119], v[52:53] op_sel_hi:[0,1,1]
	v_pk_fma_f32 v[48:49], v[176:177], v[118:119], v[48:49] op_sel_hi:[0,1,1]
	v_pk_fma_f32 v[50:51], v[174:175], v[120:121], v[50:51] op_sel_hi:[0,1,1]
	v_pk_fma_f32 v[46:47], v[176:177], v[120:121], v[46:47] op_sel_hi:[0,1,1]
	v_pk_fma_f32 v[44:45], v[174:175], v[122:123], v[44:45] op_sel_hi:[0,1,1]
	v_pk_fma_f32 v[40:41], v[176:177], v[122:123], v[40:41] op_sel_hi:[0,1,1]
	v_pk_fma_f32 v[42:43], v[174:175], v[124:125], v[42:43] op_sel_hi:[0,1,1]
	v_pk_fma_f32 v[38:39], v[176:177], v[124:125], v[38:39] op_sel_hi:[0,1,1]
	v_pk_fma_f32 v[36:37], v[174:175], v[126:127], v[36:37] op_sel_hi:[0,1,1]
	v_pk_fma_f32 v[32:33], v[176:177], v[126:127], v[32:33] op_sel_hi:[0,1,1]
	v_pk_fma_f32 v[34:35], v[174:175], v[128:129], v[34:35] op_sel_hi:[0,1,1]
	v_pk_fma_f32 v[30:31], v[176:177], v[128:129], v[30:31] op_sel_hi:[0,1,1]
	v_pk_fma_f32 v[28:29], v[174:175], v[130:131], v[28:29] op_sel_hi:[0,1,1]
	v_pk_fma_f32 v[24:25], v[176:177], v[130:131], v[24:25] op_sel_hi:[0,1,1]
	v_pk_fma_f32 v[26:27], v[174:175], v[132:133], v[26:27] op_sel_hi:[0,1,1]
	v_pk_fma_f32 v[22:23], v[176:177], v[132:133], v[22:23] op_sel_hi:[0,1,1]
	v_pk_fma_f32 v[20:21], v[174:175], v[134:135], v[20:21] op_sel_hi:[0,1,1]
	v_pk_fma_f32 v[14:15], v[176:177], v[134:135], v[14:15] op_sel_hi:[0,1,1]
	v_pk_fma_f32 v[18:19], v[174:175], v[136:137], v[18:19] op_sel_hi:[0,1,1]
	v_pk_fma_f32 v[16:17], v[176:177], v[136:137], v[16:17] op_sel_hi:[0,1,1]
	v_pk_fma_f32 v[10:11], v[174:175], v[138:139], v[10:11] op_sel_hi:[0,1,1]
	v_pk_fma_f32 v[6:7], v[176:177], v[138:139], v[6:7] op_sel_hi:[0,1,1]
	v_pk_fma_f32 v[12:13], v[174:175], v[140:141], v[12:13] op_sel_hi:[0,1,1]
	v_pk_fma_f32 v[8:9], v[176:177], v[140:141], v[8:9] op_sel_hi:[0,1,1]
	s_waitcnt vmcnt(0) lgkmcnt(0)
	v_pk_fma_f32 v[68:69], v[178:179], v[142:143], v[68:69] op_sel_hi:[0,1,1]
	v_pk_fma_f32 v[62:63], v[180:181], v[142:143], v[62:63] op_sel_hi:[0,1,1]
	v_pk_fma_f32 v[66:67], v[178:179], v[144:145], v[66:67] op_sel_hi:[0,1,1]
	v_pk_fma_f32 v[64:65], v[180:181], v[144:145], v[64:65] op_sel_hi:[0,1,1]
	v_pk_fma_f32 v[60:61], v[178:179], v[146:147], v[60:61] op_sel_hi:[0,1,1]
	v_pk_fma_f32 v[56:57], v[180:181], v[146:147], v[56:57] op_sel_hi:[0,1,1]
	v_pk_fma_f32 v[58:59], v[178:179], v[148:149], v[58:59] op_sel_hi:[0,1,1]
	v_pk_fma_f32 v[54:55], v[180:181], v[148:149], v[54:55] op_sel_hi:[0,1,1]
	v_pk_fma_f32 v[52:53], v[178:179], v[150:151], v[52:53] op_sel_hi:[0,1,1]
	v_pk_fma_f32 v[48:49], v[180:181], v[150:151], v[48:49] op_sel_hi:[0,1,1]
	v_pk_fma_f32 v[50:51], v[178:179], v[152:153], v[50:51] op_sel_hi:[0,1,1]
	v_pk_fma_f32 v[46:47], v[180:181], v[152:153], v[46:47] op_sel_hi:[0,1,1]
	v_pk_fma_f32 v[44:45], v[178:179], v[154:155], v[44:45] op_sel_hi:[0,1,1]
	v_pk_fma_f32 v[40:41], v[180:181], v[154:155], v[40:41] op_sel_hi:[0,1,1]
	v_pk_fma_f32 v[42:43], v[178:179], v[156:157], v[42:43] op_sel_hi:[0,1,1]
	v_pk_fma_f32 v[38:39], v[180:181], v[156:157], v[38:39] op_sel_hi:[0,1,1]
	v_pk_fma_f32 v[36:37], v[178:179], v[158:159], v[36:37] op_sel_hi:[0,1,1]
	v_pk_fma_f32 v[32:33], v[180:181], v[158:159], v[32:33] op_sel_hi:[0,1,1]
	v_pk_fma_f32 v[34:35], v[178:179], v[160:161], v[34:35] op_sel_hi:[0,1,1]
	v_pk_fma_f32 v[30:31], v[180:181], v[160:161], v[30:31] op_sel_hi:[0,1,1]
	v_pk_fma_f32 v[28:29], v[178:179], v[162:163], v[28:29] op_sel_hi:[0,1,1]
	v_pk_fma_f32 v[24:25], v[180:181], v[162:163], v[24:25] op_sel_hi:[0,1,1]
	v_pk_fma_f32 v[26:27], v[178:179], v[164:165], v[26:27] op_sel_hi:[0,1,1]
	v_pk_fma_f32 v[22:23], v[180:181], v[164:165], v[22:23] op_sel_hi:[0,1,1]
	v_pk_fma_f32 v[20:21], v[178:179], v[166:167], v[20:21] op_sel_hi:[0,1,1]
	v_pk_fma_f32 v[14:15], v[180:181], v[166:167], v[14:15] op_sel_hi:[0,1,1]
	v_pk_fma_f32 v[18:19], v[178:179], v[168:169], v[18:19] op_sel_hi:[0,1,1]
	v_pk_fma_f32 v[16:17], v[180:181], v[168:169], v[16:17] op_sel_hi:[0,1,1]
	v_pk_fma_f32 v[10:11], v[178:179], v[170:171], v[10:11] op_sel_hi:[0,1,1]
	v_pk_fma_f32 v[6:7], v[180:181], v[170:171], v[6:7] op_sel_hi:[0,1,1]
	v_pk_fma_f32 v[12:13], v[178:179], v[172:173], v[12:13] op_sel_hi:[0,1,1]
	v_pk_fma_f32 v[8:9], v[180:181], v[172:173], v[8:9] op_sel_hi:[0,1,1]
	s_mov_b32 s0, 0
	v_add_u32_e32 v4, 0x10000, v4
	v_cvt_f32_i32_e32 v5, s74
	s_mov_b32 s6, 0xc5fff800
	v_ashrrev_i32_e32 v3, 31, v2
	v_readlane_b32 s4, v252, 32
	v_div_scale_f32 v70, s[38:39], s6, s6, v5
	v_rcp_f32_e32 v71, v70
	v_cvt_f32_i32_e32 v4, v0
	v_lshlrev_b64 v[0:1], 15, v[0:1]
	v_readlane_b32 s5, v252, 33
	v_fma_f32 v72, -v70, v71, 1.0
	s_ashr_i32 s75, s74, 31
	v_lshlrev_b64 v[2:3], 15, v[2:3]
	v_fmac_f32_e32 v71, v72, v71
; __device__ __forceinline__ void filter_item(const Params& p, int l, int Lf, int t0, float* dst, float* hidT  , int wid0) {
;     ...
;     const float dmin = -3.0701134573253945f, dmax = -15.350567286626973f;
;     const float delta = fabsf(dmin + (float)tid * ((dmax - dmin) / 511.f));
; #pragma unroll
;     for (int g = 0; g < 8; ++g) { f32x4 o0, o1;
; #pragma unroll
;         for (int i = 0; i < 4; ++i) { const float tn = (float)(t0 + 4 * g + i) / (float)(Lf - 1); const float wdw = __expf(-tn * delta); o0[i] = acc0[4 * g + i] * wdw; o1[i] = acc1[4 * g + i] * wdw; }
;         *(f32x4*)(dst + (size_t)tid * Lf + t0 + 4 * g) = o0; *(f32x4*)(dst + (size_t)(512 + tid) * Lf + t0 + 4 * g) = o1; }
	v_div_scale_f32 v72, vcc, v5, s6, v5
	v_lshl_add_u64 v[0:1], s[4:5], 0, v[0:1]
	s_lshl_b64 s[0:1], s[74:75], 2
	v_lshl_add_u64 v[2:3], s[4:5], 0, v[2:3]
	v_mul_f32_e32 v73, v72, v71
	v_lshl_add_u64 v[0:1], v[0:1], 0, s[0:1]
	v_lshl_add_u64 v[2:3], v[2:3], 0, s[0:1]
	v_fma_f32 v74, -v70, v73, v72
	s_or_b32 s0, s74, 1
	v_fmac_f32_e32 v73, v74, v71
	v_cvt_f32_i32_e32 v74, s0
	v_fma_f32 v70, -v70, v73, v72
	v_div_fmas_f32 v70, v70, v71, v73
	v_div_fixup_f32 v5, v70, s6, v5
	v_div_scale_f32 v70, s[0:1], s6, s6, v74
	v_rcp_f32_e32 v71, v70
	v_fmamk_f32 v4, v4, 0xbcc4df2d, v219
	v_mul_f32_e64 v5, v5, |v4|
	v_mul_f32_e32 v5, 0x3fb8aa3b, v5
	v_exp_f32_e32 v72, v5
	v_fma_f32 v5, -v70, v71, 1.0
	v_fmac_f32_e32 v71, v5, v71
	v_div_scale_f32 v5, vcc, v74, s6, v74
	v_mul_f32_e32 v73, v5, v71
	v_fma_f32 v75, -v70, v73, v5
	v_fmac_f32_e32 v73, v75, v71
	s_or_b32 s0, s74, 2
	v_fma_f32 v5, -v70, v73, v5
	v_cvt_f32_i32_e32 v70, s0
	v_div_fmas_f32 v5, v5, v71, v73
	v_div_fixup_f32 v5, v5, s6, v74
	v_mul_f32_e64 v5, v5, |v4|
	v_div_scale_f32 v71, s[0:1], s6, s6, v70
	v_rcp_f32_e32 v74, v71
	v_mul_f32_e32 v5, 0x3fb8aa3b, v5
	v_exp_f32_e32 v73, v5
	s_or_b32 s0, s74, 3
	v_fma_f32 v5, -v71, v74, 1.0
	v_fmac_f32_e32 v74, v5, v74
	v_div_scale_f32 v5, vcc, v70, s6, v70
	v_mul_f32_e32 v75, v5, v74
	v_fma_f32 v76, -v71, v75, v5
	v_fmac_f32_e32 v75, v76, v74
	v_fma_f32 v5, -v71, v75, v5
	v_cvt_f32_i32_e32 v71, s0
	v_div_fmas_f32 v5, v5, v74, v75
	v_div_fixup_f32 v5, v5, s6, v70
	v_mul_f32_e64 v5, v5, |v4|
	v_div_scale_f32 v70, s[0:1], s6, s6, v71
	v_rcp_f32_e32 v75, v70
	v_mul_f32_e32 v5, 0x3fb8aa3b, v5
	v_exp_f32_e32 v74, v5
	s_or_b32 s0, s74, 4
	v_fma_f32 v5, -v70, v75, 1.0
	v_fmac_f32_e32 v75, v5, v75
	v_div_scale_f32 v5, vcc, v71, s6, v71
	v_mul_f32_e32 v76, v5, v75
	v_fma_f32 v77, -v70, v76, v5
	v_fmac_f32_e32 v76, v77, v75
	v_fma_f32 v5, -v70, v76, v5
	v_div_fmas_f32 v5, v5, v75, v76
	v_div_fixup_f32 v5, v5, s6, v71
	v_mul_f32_e64 v5, v5, |v4|
	v_mul_f32_e32 v5, 0x3fb8aa3b, v5
	v_exp_f32_e32 v75, v5
	v_cvt_f32_i32_e32 v5, s0
	v_pk_mul_f32 v[68:69], v[72:73], v[68:69]
	v_pk_mul_f32 v[62:63], v[72:73], v[62:63]
	v_pk_mul_f32 v[70:71], v[74:75], v[66:67]
	v_div_scale_f32 v66, s[0:1], s6, s6, v5
	v_rcp_f32_e32 v67, v66
	v_pk_mul_f32 v[64:65], v[74:75], v[64:65]
	global_store_dwordx4 v[0:1], v[68:71], off
	global_store_dwordx4 v[2:3], v[62:65], off
	s_or_b32 s0, s74, 5
	s_add_i32 s26, s26, s24
	v_fma_f32 v62, -v66, v67, 1.0
	v_fmac_f32_e32 v67, v62, v67
	v_div_scale_f32 v62, vcc, v5, s6, v5
	v_mul_f32_e32 v63, v62, v67
	v_fma_f32 v64, -v66, v63, v62
	v_cvt_f32_i32_e32 v65, s0
	v_fmac_f32_e32 v63, v64, v67
	v_fma_f32 v62, -v66, v63, v62
	v_div_fmas_f32 v62, v62, v67, v63
	v_div_fixup_f32 v5, v62, s6, v5
	v_div_scale_f32 v62, s[0:1], s6, s6, v65
	v_rcp_f32_e32 v63, v62
	v_mul_f32_e64 v5, v5, |v4|
	v_mul_f32_e32 v5, 0x3fb8aa3b, v5
	v_exp_f32_e32 v64, v5
	v_fma_f32 v5, -v62, v63, 1.0
	v_fmac_f32_e32 v63, v5, v63
	v_div_scale_f32 v5, vcc, v65, s6, v65
	v_mul_f32_e32 v66, v5, v63
	v_fma_f32 v67, -v62, v66, v5
	v_fmac_f32_e32 v66, v67, v63
	s_or_b32 s0, s74, 6
	v_fma_f32 v5, -v62, v66, v5
	v_cvt_f32_i32_e32 v62, s0
	v_div_fmas_f32 v5, v5, v63, v66
	v_div_fixup_f32 v5, v5, s6, v65
	v_mul_f32_e64 v5, v5, |v4|
	v_div_scale_f32 v63, s[0:1], s6, s6, v62
	v_rcp_f32_e32 v66, v63
	v_mul_f32_e32 v5, 0x3fb8aa3b, v5
	v_exp_f32_e32 v65, v5
	s_or_b32 s0, s74, 7
	v_fma_f32 v5, -v63, v66, 1.0
	v_fmac_f32_e32 v66, v5, v66
	v_div_scale_f32 v5, vcc, v62, s6, v62
	v_mul_f32_e32 v67, v5, v66
	v_fma_f32 v68, -v63, v67, v5
	v_fmac_f32_e32 v67, v68, v66
	v_fma_f32 v5, -v63, v67, v5
	v_cvt_f32_i32_e32 v63, s0
	v_div_fmas_f32 v5, v5, v66, v67
	v_div_fixup_f32 v5, v5, s6, v62
	v_mul_f32_e64 v5, v5, |v4|
	v_div_scale_f32 v62, s[0:1], s6, s6, v63
	v_rcp_f32_e32 v67, v62
	v_mul_f32_e32 v5, 0x3fb8aa3b, v5
	v_exp_f32_e32 v66, v5
	s_or_b32 s0, s74, 8
	v_fma_f32 v5, -v62, v67, 1.0
	v_fmac_f32_e32 v67, v5, v67
	v_div_scale_f32 v5, vcc, v63, s6, v63
	v_mul_f32_e32 v68, v5, v67
	v_fma_f32 v69, -v62, v68, v5
	v_fmac_f32_e32 v68, v69, v67
	v_fma_f32 v5, -v62, v68, v5
	v_div_fmas_f32 v5, v5, v67, v68
	v_div_fixup_f32 v5, v5, s6, v63
	v_mul_f32_e64 v5, v5, |v4|
	v_mul_f32_e32 v5, 0x3fb8aa3b, v5
	v_exp_f32_e32 v67, v5
	v_cvt_f32_i32_e32 v5, s0
	v_pk_mul_f32 v[60:61], v[64:65], v[60:61]
	v_pk_mul_f32 v[56:57], v[64:65], v[56:57]
	v_pk_mul_f32 v[62:63], v[66:67], v[58:59]
	v_div_scale_f32 v64, s[0:1], s6, s6, v5
	v_rcp_f32_e32 v65, v64
	v_pk_mul_f32 v[58:59], v[66:67], v[54:55]
	s_or_b32 s0, s74, 9
	global_store_dwordx4 v[0:1], v[60:63], off offset:16
	global_store_dwordx4 v[2:3], v[56:59], off offset:16
	v_fma_f32 v54, -v64, v65, 1.0
	v_fmac_f32_e32 v65, v54, v65
	v_div_scale_f32 v54, vcc, v5, s6, v5
	v_mul_f32_e32 v55, v54, v65
	v_fma_f32 v56, -v64, v55, v54
	v_cvt_f32_i32_e32 v57, s0
	v_fmac_f32_e32 v55, v56, v65
	v_fma_f32 v54, -v64, v55, v54
	v_div_fmas_f32 v54, v54, v65, v55
	v_div_fixup_f32 v5, v54, s6, v5
	v_div_scale_f32 v54, s[0:1], s6, s6, v57
	v_rcp_f32_e32 v55, v54
	v_mul_f32_e64 v5, v5, |v4|
	v_mul_f32_e32 v5, 0x3fb8aa3b, v5
	v_exp_f32_e32 v56, v5
	v_fma_f32 v5, -v54, v55, 1.0
	v_fmac_f32_e32 v55, v5, v55
	v_div_scale_f32 v5, vcc, v57, s6, v57
	v_mul_f32_e32 v58, v5, v55
	v_fma_f32 v59, -v54, v58, v5
	v_fmac_f32_e32 v58, v59, v55
	s_or_b32 s0, s74, 10
	v_fma_f32 v5, -v54, v58, v5
	v_cvt_f32_i32_e32 v54, s0
	v_div_fmas_f32 v5, v5, v55, v58
	v_div_fixup_f32 v5, v5, s6, v57
	v_mul_f32_e64 v5, v5, |v4|
	v_div_scale_f32 v55, s[0:1], s6, s6, v54
	v_rcp_f32_e32 v58, v55
	v_mul_f32_e32 v5, 0x3fb8aa3b, v5
	v_exp_f32_e32 v57, v5
	s_or_b32 s0, s74, 11
	v_fma_f32 v5, -v55, v58, 1.0
	v_fmac_f32_e32 v58, v5, v58
; __device__ __forceinline__ void filter_item(const Params& p, int l, int Lf, int t0, float* dst, float* hidT  , int wid0) {
;     ...
;     const float dmin = -3.0701134573253945f, dmax = -15.350567286626973f;
;     const float delta = fabsf(dmin + (float)tid * ((dmax - dmin) / 511.f));
; #pragma unroll
;     for (int g = 0; g < 8; ++g) { f32x4 o0, o1;
; #pragma unroll
;         for (int i = 0; i < 4; ++i) { const float tn = (float)(t0 + 4 * g + i) / (float)(Lf - 1); const float wdw = __expf(-tn * delta); o0[i] = acc0[4 * g + i] * wdw; o1[i] = acc1[4 * g + i] * wdw; }
;         *(f32x4*)(dst + (size_t)tid * Lf + t0 + 4 * g) = o0; *(f32x4*)(dst + (size_t)(512 + tid) * Lf + t0 + 4 * g) = o1; }
	v_div_scale_f32 v5, vcc, v54, s6, v54
	v_mul_f32_e32 v59, v5, v58
	v_fma_f32 v60, -v55, v59, v5
	v_fmac_f32_e32 v59, v60, v58
	v_fma_f32 v5, -v55, v59, v5
	v_cvt_f32_i32_e32 v55, s0
	v_div_fmas_f32 v5, v5, v58, v59
	v_div_fixup_f32 v5, v5, s6, v54
	v_mul_f32_e64 v5, v5, |v4|
	v_div_scale_f32 v54, s[0:1], s6, s6, v55
	v_rcp_f32_e32 v59, v54
	v_mul_f32_e32 v5, 0x3fb8aa3b, v5
	v_exp_f32_e32 v58, v5
	s_or_b32 s0, s74, 12
	v_fma_f32 v5, -v54, v59, 1.0
	v_fmac_f32_e32 v59, v5, v59
	v_div_scale_f32 v5, vcc, v55, s6, v55
	v_mul_f32_e32 v60, v5, v59
	v_fma_f32 v61, -v54, v60, v5
	v_fmac_f32_e32 v60, v61, v59
	v_fma_f32 v5, -v54, v60, v5
	v_div_fmas_f32 v5, v5, v59, v60
	v_div_fixup_f32 v5, v5, s6, v55
	v_mul_f32_e64 v5, v5, |v4|
	v_mul_f32_e32 v5, 0x3fb8aa3b, v5
	v_exp_f32_e32 v59, v5
	v_cvt_f32_i32_e32 v5, s0
	v_pk_mul_f32 v[52:53], v[56:57], v[52:53]
	v_pk_mul_f32 v[48:49], v[56:57], v[48:49]
	v_pk_mul_f32 v[54:55], v[58:59], v[50:51]
	v_div_scale_f32 v56, s[0:1], s6, s6, v5
	v_rcp_f32_e32 v57, v56
	v_pk_mul_f32 v[50:51], v[58:59], v[46:47]
	s_or_b32 s0, s74, 13
	global_store_dwordx4 v[0:1], v[52:55], off offset:32
	global_store_dwordx4 v[2:3], v[48:51], off offset:32
	v_fma_f32 v46, -v56, v57, 1.0
	v_fmac_f32_e32 v57, v46, v57
	v_div_scale_f32 v46, vcc, v5, s6, v5
	v_mul_f32_e32 v47, v46, v57
	v_fma_f32 v48, -v56, v47, v46
	v_cvt_f32_i32_e32 v49, s0
	v_fmac_f32_e32 v47, v48, v57
	v_fma_f32 v46, -v56, v47, v46
	v_div_fmas_f32 v46, v46, v57, v47
	v_div_fixup_f32 v5, v46, s6, v5
	v_div_scale_f32 v46, s[0:1], s6, s6, v49
	v_rcp_f32_e32 v47, v46
	v_mul_f32_e64 v5, v5, |v4|
	v_mul_f32_e32 v5, 0x3fb8aa3b, v5
	v_exp_f32_e32 v48, v5
	v_fma_f32 v5, -v46, v47, 1.0
	v_fmac_f32_e32 v47, v5, v47
	v_div_scale_f32 v5, vcc, v49, s6, v49
	v_mul_f32_e32 v50, v5, v47
	v_fma_f32 v51, -v46, v50, v5
	v_fmac_f32_e32 v50, v51, v47
	s_or_b32 s0, s74, 14
	v_fma_f32 v5, -v46, v50, v5
	v_cvt_f32_i32_e32 v46, s0
	v_div_fmas_f32 v5, v5, v47, v50
	v_div_fixup_f32 v5, v5, s6, v49
	v_mul_f32_e64 v5, v5, |v4|
	v_div_scale_f32 v47, s[0:1], s6, s6, v46
	v_rcp_f32_e32 v50, v47
	v_mul_f32_e32 v5, 0x3fb8aa3b, v5
	v_exp_f32_e32 v49, v5
	s_or_b32 s0, s74, 15
	v_fma_f32 v5, -v47, v50, 1.0
	v_fmac_f32_e32 v50, v5, v50
	v_div_scale_f32 v5, vcc, v46, s6, v46
	v_mul_f32_e32 v51, v5, v50
	v_fma_f32 v52, -v47, v51, v5
	v_fmac_f32_e32 v51, v52, v50
	v_fma_f32 v5, -v47, v51, v5
	v_cvt_f32_i32_e32 v47, s0
	v_div_fmas_f32 v5, v5, v50, v51
	v_div_fixup_f32 v5, v5, s6, v46
	v_mul_f32_e64 v5, v5, |v4|
	v_div_scale_f32 v46, s[0:1], s6, s6, v47
	v_rcp_f32_e32 v51, v46
	v_mul_f32_e32 v5, 0x3fb8aa3b, v5
	v_exp_f32_e32 v50, v5
	s_or_b32 s0, s74, 16
	v_fma_f32 v5, -v46, v51, 1.0
	v_fmac_f32_e32 v51, v5, v51
	v_div_scale_f32 v5, vcc, v47, s6, v47
	v_mul_f32_e32 v52, v5, v51
	v_fma_f32 v53, -v46, v52, v5
	v_fmac_f32_e32 v52, v53, v51
	v_fma_f32 v5, -v46, v52, v5
	v_div_fmas_f32 v5, v5, v51, v52
	v_div_fixup_f32 v5, v5, s6, v47
	v_mul_f32_e64 v5, v5, |v4|
	v_mul_f32_e32 v5, 0x3fb8aa3b, v5
	v_exp_f32_e32 v51, v5
	v_cvt_f32_i32_e32 v5, s0
	v_pk_mul_f32 v[44:45], v[48:49], v[44:45]
	v_pk_mul_f32 v[40:41], v[48:49], v[40:41]
	v_pk_mul_f32 v[46:47], v[50:51], v[42:43]
	v_div_scale_f32 v48, s[0:1], s6, s6, v5
	v_rcp_f32_e32 v49, v48
	v_pk_mul_f32 v[42:43], v[50:51], v[38:39]
	s_or_b32 s0, s74, 17
	global_store_dwordx4 v[0:1], v[44:47], off offset:48
	global_store_dwordx4 v[2:3], v[40:43], off offset:48
	v_fma_f32 v38, -v48, v49, 1.0
	v_fmac_f32_e32 v49, v38, v49
	v_div_scale_f32 v38, vcc, v5, s6, v5
	v_mul_f32_e32 v39, v38, v49
	v_fma_f32 v40, -v48, v39, v38
	v_cvt_f32_i32_e32 v41, s0
	v_fmac_f32_e32 v39, v40, v49
	v_fma_f32 v38, -v48, v39, v38
	v_div_fmas_f32 v38, v38, v49, v39
	v_div_fixup_f32 v5, v38, s6, v5
	v_div_scale_f32 v38, s[0:1], s6, s6, v41
	v_rcp_f32_e32 v39, v38
	v_mul_f32_e64 v5, v5, |v4|
	v_mul_f32_e32 v5, 0x3fb8aa3b, v5
	v_exp_f32_e32 v40, v5
	v_fma_f32 v5, -v38, v39, 1.0
	v_fmac_f32_e32 v39, v5, v39
	v_div_scale_f32 v5, vcc, v41, s6, v41
	v_mul_f32_e32 v42, v5, v39
	v_fma_f32 v43, -v38, v42, v5
	v_fmac_f32_e32 v42, v43, v39
	s_or_b32 s0, s74, 18
	v_fma_f32 v5, -v38, v42, v5
	v_cvt_f32_i32_e32 v38, s0
	v_div_fmas_f32 v5, v5, v39, v42
	v_div_fixup_f32 v5, v5, s6, v41
	v_mul_f32_e64 v5, v5, |v4|
	v_div_scale_f32 v39, s[0:1], s6, s6, v38
	v_rcp_f32_e32 v42, v39
	v_mul_f32_e32 v5, 0x3fb8aa3b, v5
	v_exp_f32_e32 v41, v5
	s_or_b32 s0, s74, 19
	v_fma_f32 v5, -v39, v42, 1.0
	v_fmac_f32_e32 v42, v5, v42
	v_div_scale_f32 v5, vcc, v38, s6, v38
	v_mul_f32_e32 v43, v5, v42
	v_fma_f32 v44, -v39, v43, v5
	v_fmac_f32_e32 v43, v44, v42
	v_fma_f32 v5, -v39, v43, v5
	v_cvt_f32_i32_e32 v39, s0
	v_div_fmas_f32 v5, v5, v42, v43
	v_div_fixup_f32 v5, v5, s6, v38
	v_mul_f32_e64 v5, v5, |v4|
	v_div_scale_f32 v38, s[0:1], s6, s6, v39
	v_rcp_f32_e32 v43, v38
	v_mul_f32_e32 v5, 0x3fb8aa3b, v5
	v_exp_f32_e32 v42, v5
	s_or_b32 s0, s74, 20
	v_fma_f32 v5, -v38, v43, 1.0
	v_fmac_f32_e32 v43, v5, v43
	v_div_scale_f32 v5, vcc, v39, s6, v39
	v_mul_f32_e32 v44, v5, v43
	v_fma_f32 v45, -v38, v44, v5
	v_fmac_f32_e32 v44, v45, v43
	v_fma_f32 v5, -v38, v44, v5
	v_div_fmas_f32 v5, v5, v43, v44
	v_div_fixup_f32 v5, v5, s6, v39
	v_mul_f32_e64 v5, v5, |v4|
	v_mul_f32_e32 v5, 0x3fb8aa3b, v5
	v_exp_f32_e32 v43, v5
	v_cvt_f32_i32_e32 v5, s0
	v_pk_mul_f32 v[36:37], v[40:41], v[36:37]
	v_pk_mul_f32 v[32:33], v[40:41], v[32:33]
	v_pk_mul_f32 v[38:39], v[42:43], v[34:35]
	v_div_scale_f32 v40, s[0:1], s6, s6, v5
	v_rcp_f32_e32 v41, v40
	v_pk_mul_f32 v[34:35], v[42:43], v[30:31]
	s_or_b32 s0, s74, 21
	global_store_dwordx4 v[0:1], v[36:39], off offset:64
	global_store_dwordx4 v[2:3], v[32:35], off offset:64
	v_fma_f32 v30, -v40, v41, 1.0
; __device__ __forceinline__ void filter_item(const Params& p, int l, int Lf, int t0, float* dst, float* hidT  , int wid0) {
;     ...
;     const float dmin = -3.0701134573253945f, dmax = -15.350567286626973f;
;     const float delta = fabsf(dmin + (float)tid * ((dmax - dmin) / 511.f));
; #pragma unroll
;     for (int g = 0; g < 8; ++g) { f32x4 o0, o1;
; #pragma unroll
;         for (int i = 0; i < 4; ++i) { const float tn = (float)(t0 + 4 * g + i) / (float)(Lf - 1); const float wdw = __expf(-tn * delta); o0[i] = acc0[4 * g + i] * wdw; o1[i] = acc1[4 * g + i] * wdw; }
;         *(f32x4*)(dst + (size_t)tid * Lf + t0 + 4 * g) = o0; *(f32x4*)(dst + (size_t)(512 + tid) * Lf + t0 + 4 * g) = o1; }
;     __syncthreads();
; __device__ __forceinline__ void phaseA(const Params& p, int l, unsigned char* lds, int wid0) {
;     ...
;     { float* hidT = (float*)(lds + 104448);
;       for (int it = blockIdx.x; it < 256; it += gridDim.x) filter_item(p, l, SEQ, 32 * it, (float*)(ws + WS_FILT), hidT, wid0);
;       }
	v_fmac_f32_e32 v41, v30, v41
	v_div_scale_f32 v30, vcc, v5, s6, v5
	v_mul_f32_e32 v31, v30, v41
	v_fma_f32 v32, -v40, v31, v30
	v_cvt_f32_i32_e32 v33, s0
	v_fmac_f32_e32 v31, v32, v41
	v_fma_f32 v30, -v40, v31, v30
	v_div_fmas_f32 v30, v30, v41, v31
	v_div_fixup_f32 v5, v30, s6, v5
	v_div_scale_f32 v30, s[0:1], s6, s6, v33
	v_rcp_f32_e32 v31, v30
	v_mul_f32_e64 v5, v5, |v4|
	v_mul_f32_e32 v5, 0x3fb8aa3b, v5
	v_exp_f32_e32 v32, v5
	v_fma_f32 v5, -v30, v31, 1.0
	v_fmac_f32_e32 v31, v5, v31
	v_div_scale_f32 v5, vcc, v33, s6, v33
	v_mul_f32_e32 v34, v5, v31
	v_fma_f32 v35, -v30, v34, v5
	v_fmac_f32_e32 v34, v35, v31
	s_or_b32 s0, s74, 22
	v_fma_f32 v5, -v30, v34, v5
	v_cvt_f32_i32_e32 v30, s0
	v_div_fmas_f32 v5, v5, v31, v34
	v_div_fixup_f32 v5, v5, s6, v33
	v_mul_f32_e64 v5, v5, |v4|
	v_div_scale_f32 v31, s[0:1], s6, s6, v30
	v_rcp_f32_e32 v34, v31
	v_mul_f32_e32 v5, 0x3fb8aa3b, v5
	v_exp_f32_e32 v33, v5
	s_or_b32 s0, s74, 23
	v_fma_f32 v5, -v31, v34, 1.0
	v_fmac_f32_e32 v34, v5, v34
	v_div_scale_f32 v5, vcc, v30, s6, v30
	v_mul_f32_e32 v35, v5, v34
	v_fma_f32 v36, -v31, v35, v5
	v_fmac_f32_e32 v35, v36, v34
	v_fma_f32 v5, -v31, v35, v5
	v_cvt_f32_i32_e32 v31, s0
	v_div_fmas_f32 v5, v5, v34, v35
	v_div_fixup_f32 v5, v5, s6, v30
	v_mul_f32_e64 v5, v5, |v4|
	v_div_scale_f32 v30, s[0:1], s6, s6, v31
	v_rcp_f32_e32 v35, v30
	v_mul_f32_e32 v5, 0x3fb8aa3b, v5
	v_exp_f32_e32 v34, v5
	s_or_b32 s0, s74, 24
	v_fma_f32 v5, -v30, v35, 1.0
	v_fmac_f32_e32 v35, v5, v35
	v_div_scale_f32 v5, vcc, v31, s6, v31
	v_mul_f32_e32 v36, v5, v35
	v_fma_f32 v37, -v30, v36, v5
	v_fmac_f32_e32 v36, v37, v35
	v_fma_f32 v5, -v30, v36, v5
	v_div_fmas_f32 v5, v5, v35, v36
	v_div_fixup_f32 v5, v5, s6, v31
	v_mul_f32_e64 v5, v5, |v4|
	v_mul_f32_e32 v5, 0x3fb8aa3b, v5
	v_exp_f32_e32 v35, v5
	v_cvt_f32_i32_e32 v5, s0
	v_pk_mul_f32 v[28:29], v[32:33], v[28:29]
	v_pk_mul_f32 v[24:25], v[32:33], v[24:25]
	v_pk_mul_f32 v[30:31], v[34:35], v[26:27]
	v_div_scale_f32 v32, s[0:1], s6, s6, v5
	v_rcp_f32_e32 v33, v32
	v_pk_mul_f32 v[26:27], v[34:35], v[22:23]
	s_or_b32 s0, s74, 25
	global_store_dwordx4 v[0:1], v[28:31], off offset:80
	global_store_dwordx4 v[2:3], v[24:27], off offset:80
	v_fma_f32 v22, -v32, v33, 1.0
	v_fmac_f32_e32 v33, v22, v33
	v_div_scale_f32 v22, vcc, v5, s6, v5
	v_mul_f32_e32 v23, v22, v33
	v_fma_f32 v24, -v32, v23, v22
	v_cvt_f32_i32_e32 v25, s0
	v_fmac_f32_e32 v23, v24, v33
	v_fma_f32 v22, -v32, v23, v22
	v_div_fmas_f32 v22, v22, v33, v23
	v_div_fixup_f32 v5, v22, s6, v5
	v_div_scale_f32 v22, s[0:1], s6, s6, v25
	v_rcp_f32_e32 v23, v22
	v_mul_f32_e64 v5, v5, |v4|
	v_mul_f32_e32 v5, 0x3fb8aa3b, v5
	v_exp_f32_e32 v24, v5
	v_fma_f32 v5, -v22, v23, 1.0
	v_fmac_f32_e32 v23, v5, v23
	v_div_scale_f32 v5, vcc, v25, s6, v25
	v_mul_f32_e32 v26, v5, v23
	v_fma_f32 v27, -v22, v26, v5
	v_fmac_f32_e32 v26, v27, v23
	s_or_b32 s0, s74, 26
	v_fma_f32 v5, -v22, v26, v5
	v_cvt_f32_i32_e32 v22, s0
	v_div_fmas_f32 v5, v5, v23, v26
	v_div_fixup_f32 v5, v5, s6, v25
	v_mul_f32_e64 v5, v5, |v4|
	v_div_scale_f32 v23, s[0:1], s6, s6, v22
	v_rcp_f32_e32 v26, v23
	v_mul_f32_e32 v5, 0x3fb8aa3b, v5
	v_exp_f32_e32 v25, v5
	s_or_b32 s0, s74, 27
	v_fma_f32 v5, -v23, v26, 1.0
	v_fmac_f32_e32 v26, v5, v26
	v_div_scale_f32 v5, vcc, v22, s6, v22
	v_mul_f32_e32 v27, v5, v26
	v_fma_f32 v28, -v23, v27, v5
	v_fmac_f32_e32 v27, v28, v26
	v_fma_f32 v5, -v23, v27, v5
	v_cvt_f32_i32_e32 v23, s0
	v_div_fmas_f32 v5, v5, v26, v27
	v_div_fixup_f32 v5, v5, s6, v22
	v_mul_f32_e64 v5, v5, |v4|
	v_div_scale_f32 v22, s[0:1], s6, s6, v23
	v_rcp_f32_e32 v27, v22
	v_mul_f32_e32 v5, 0x3fb8aa3b, v5
	v_exp_f32_e32 v26, v5
	s_or_b32 s0, s74, 28
	v_fma_f32 v5, -v22, v27, 1.0
	v_fmac_f32_e32 v27, v5, v27
	v_div_scale_f32 v5, vcc, v23, s6, v23
	v_mul_f32_e32 v28, v5, v27
	v_fma_f32 v29, -v22, v28, v5
	v_fmac_f32_e32 v28, v29, v27
	v_fma_f32 v5, -v22, v28, v5
	v_div_fmas_f32 v5, v5, v27, v28
	v_cvt_f32_i32_e32 v28, s0
	v_div_fixup_f32 v5, v5, s6, v23
	v_mul_f32_e64 v5, v5, |v4|
	v_mul_f32_e32 v5, 0x3fb8aa3b, v5
	v_exp_f32_e32 v27, v5
	v_div_scale_f32 v5, s[0:1], s6, s6, v28
	v_rcp_f32_e32 v29, v5
	v_pk_mul_f32 v[22:23], v[26:27], v[18:19]
	v_pk_mul_f32 v[20:21], v[24:25], v[20:21]
	v_pk_mul_f32 v[14:15], v[24:25], v[14:15]
	v_fma_f32 v18, -v5, v29, 1.0
	v_fmac_f32_e32 v29, v18, v29
	v_div_scale_f32 v18, vcc, v28, s6, v28
	v_mul_f32_e32 v19, v18, v29
	v_fma_f32 v24, -v5, v19, v18
	s_or_b32 s0, s74, 29
	v_fmac_f32_e32 v19, v24, v29
	v_cvt_f32_i32_e32 v24, s0
	v_fma_f32 v5, -v5, v19, v18
	v_div_fmas_f32 v5, v5, v29, v19
	v_div_fixup_f32 v5, v5, s6, v28
	v_div_scale_f32 v19, s[0:1], s6, s6, v24
	v_rcp_f32_e32 v25, v19
	v_mul_f32_e64 v5, v5, |v4|
	v_mul_f32_e32 v5, 0x3fb8aa3b, v5
	v_exp_f32_e32 v18, v5
	v_fma_f32 v5, -v19, v25, 1.0
	v_fmac_f32_e32 v25, v5, v25
	v_div_scale_f32 v5, vcc, v24, s6, v24
	v_pk_mul_f32 v[16:17], v[26:27], v[16:17]
	v_mul_f32_e32 v26, v5, v25
	v_fma_f32 v27, -v19, v26, v5
	s_or_b32 s0, s74, 30
	v_fmac_f32_e32 v26, v27, v25
	v_cvt_f32_i32_e32 v27, s0
	v_fma_f32 v5, -v19, v26, v5
	v_div_fmas_f32 v5, v5, v25, v26
	v_div_fixup_f32 v5, v5, s6, v24
	v_div_scale_f32 v24, s[0:1], s6, s6, v27
	v_rcp_f32_e32 v25, v24
	v_mul_f32_e64 v5, v5, |v4|
	v_mul_f32_e32 v5, 0x3fb8aa3b, v5
	v_exp_f32_e32 v19, v5
	v_fma_f32 v5, -v24, v25, 1.0
	v_fmac_f32_e32 v25, v5, v25
	v_div_scale_f32 v5, vcc, v27, s6, v27
	v_mul_f32_e32 v26, v5, v25
	v_fma_f32 v28, -v24, v26, v5
	s_or_b32 s0, s74, 31
	v_fmac_f32_e32 v26, v28, v25
	v_cvt_f32_i32_e32 v28, s0
	v_fma_f32 v5, -v24, v26, v5
	v_div_fmas_f32 v5, v5, v25, v26
	v_div_fixup_f32 v5, v5, s6, v27
	v_div_scale_f32 v25, s[0:1], s6, s6, v28
	v_rcp_f32_e32 v26, v25
	v_mul_f32_e64 v5, v5, |v4|
	v_mul_f32_e32 v5, 0x3fb8aa3b, v5
	v_exp_f32_e32 v24, v5
	v_fma_f32 v5, -v25, v26, 1.0
	v_fmac_f32_e32 v26, v5, v26
	v_div_scale_f32 v5, vcc, v28, s6, v28
	v_mul_f32_e32 v27, v5, v26
	v_fma_f32 v29, -v25, v27, v5
	v_fmac_f32_e32 v27, v29, v26
	v_fma_f32 v5, -v25, v27, v5
	v_div_fmas_f32 v5, v5, v26, v27
	v_div_fixup_f32 v5, v5, s6, v28
	v_mul_f32_e64 v4, v5, |v4|
	v_mul_f32_e32 v4, 0x3fb8aa3b, v4
	v_exp_f32_e32 v25, v4
	v_pk_mul_f32 v[10:11], v[18:19], v[10:11]
	s_cmpk_gt_i32 s26, 0xff
	s_mov_b32 s75, 0x18000
	v_pk_mul_f32 v[12:13], v[24:25], v[12:13]
	global_store_dwordx4 v[0:1], v[20:23], off offset:96
	global_store_dwordx4 v[2:3], v[14:17], off offset:96
	v_pk_mul_f32 v[4:5], v[18:19], v[6:7]
	v_pk_mul_f32 v[6:7], v[24:25], v[8:9]
	global_store_dwordx4 v[0:1], v[10:13], off offset:112
	global_store_dwordx4 v[2:3], v[4:7], off offset:112
	s_barrier
	s_cbranch_scc0 .LBB0_592
	s_branch .LBB0_725
